# dense attention MFMA segment: 4 fragment buffers, reads three fragments ahead (v61 + n4 + a3)
# speedup vs baseline: 1.0419x; 1.0035x over previous
.LBB0_1013:
	s_waitcnt lgkmcnt(2)
	v_mfma_f32_32x32x16_bf16 v[50:65], v[226:229], v[170:173], v[50:65]
	ds_read_b128 v[240:243], v235 offset:4640
	v_mfma_f32_32x32x16_bf16 v[16:31], v[226:229], v[174:177], v[16:31]
	s_add_i32 s44, s4, 1
	s_and_b32 s43, s44, 1
	s_mul_i32 s43, s43, 0x2400
	s_waitcnt lgkmcnt(2)
	v_mfma_f32_32x32x16_bf16 v[34:49], v[230:233], v[170:173], v[34:49]
	ds_read_b128 v[226:229], v235 offset:64
	v_add_u32_e32 v198, s43, v203
	v_add_u32_e32 v199, s42, v203
	v_mfma_f32_32x32x16_bf16 v[0:15], v[230:233], v[174:177], v[0:15]
	s_add_i32 s16, s4, 2
	s_min_u32 s16, s16, 63
	s_waitcnt lgkmcnt(2)
	v_mfma_f32_32x32x16_bf16 v[50:65], v[246:249], v[166:169], v[50:65]
	ds_read_b128 v[230:233], v235 offset:4672
	v_mfma_f32_32x32x16_bf16 v[16:31], v[246:249], v[162:165], v[16:31]
	s_waitcnt lgkmcnt(2)
	v_mfma_f32_32x32x16_bf16 v[34:49], v[240:243], v[166:169], v[34:49]
	ds_read_b128 v[246:249], v235 offset:96
	v_mfma_f32_32x32x16_bf16 v[0:15], v[240:243], v[162:165], v[0:15]
	s_waitcnt lgkmcnt(2)
	v_mfma_f32_32x32x16_bf16 v[50:65], v[226:229], v[186:189], v[50:65]
	ds_read_b128 v[240:243], v235 offset:4704
	v_mfma_f32_32x32x16_bf16 v[16:31], v[226:229], v[218:221], v[16:31]
	s_waitcnt lgkmcnt(2)
	v_mfma_f32_32x32x16_bf16 v[34:49], v[230:233], v[186:189], v[34:49]
	ds_read_b128 v[226:229], v234
	v_mfma_f32_32x32x16_bf16 v[0:15], v[230:233], v[218:221], v[0:15]
	s_waitcnt lgkmcnt(2)
	v_mfma_f32_32x32x16_bf16 v[50:65], v[246:249], v[190:193], v[50:65]
	ds_read_b128 v[230:233], v234 offset:32
	v_mfma_f32_32x32x16_bf16 v[16:31], v[246:249], v[222:225], v[16:31]
	s_waitcnt lgkmcnt(2)
	v_mfma_f32_32x32x16_bf16 v[34:49], v[240:243], v[190:193], v[34:49]
	ds_read_b128 v[246:249], v234 offset:64
	v_mfma_f32_32x32x16_bf16 v[0:15], v[240:243], v[222:225], v[0:15]
	s_waitcnt lgkmcnt(2)
	v_mfma_f32_32x32x16_bf16 v[114:129], v[226:229], v[130:133], 0
	ds_read_b128 v[240:243], v234 offset:96
	v_mfma_f32_32x32x16_bf16 v[98:113], v[226:229], v[146:149], 0
	s_waitcnt lgkmcnt(2)
	v_mfma_f32_32x32x16_bf16 v[114:129], v[230:233], v[134:137], v[114:129]
	ds_read_b128 v[226:229], v234 offset:4608
	s_waitcnt vmcnt(0)
	ds_write_b128 v199, v[178:181]
	v_mfma_f32_32x32x16_bf16 v[98:113], v[230:233], v[150:153], v[98:113]
	s_waitcnt lgkmcnt(3)
	v_mfma_f32_32x32x16_bf16 v[114:129], v[246:249], v[138:141], v[114:129]
	ds_read_b128 v[230:233], v234 offset:4640
	ds_write_b128 v198, v[182:185]
	v_mfma_f32_32x32x16_bf16 v[98:113], v[246:249], v[154:157], v[98:113]
	s_waitcnt lgkmcnt(4)
	v_mfma_f32_32x32x16_bf16 v[114:129], v[240:243], v[142:145], v[114:129]
	ds_read_b128 v[246:249], v234 offset:4672
	s_lshl_b64 s[6:7], s[16:17], 13
	v_lshl_add_u64 v[182:183], v[212:213], 0, s[6:7]
	v_mfma_f32_32x32x16_bf16 v[98:113], v[240:243], v[158:161], v[98:113]
	global_load_dwordx4 v[182:185], v[182:183], off
	s_lshl_b64 s[6:7], s[16:17], 7
	s_waitcnt lgkmcnt(4)
	v_mfma_f32_32x32x16_bf16 v[82:97], v[226:229], v[130:133], 0
	ds_read_b128 v[240:243], v234 offset:4704
	v_lshl_add_u64 v[178:179], v[214:215], 0, s[6:7]
	v_mfma_f32_32x32x16_bf16 v[66:81], v[226:229], v[146:149], 0
	global_load_dwordx4 v[178:181], v[178:179], off
	s_waitcnt lgkmcnt(3)
	v_mfma_f32_32x32x16_bf16 v[82:97], v[230:233], v[134:137], v[82:97]
	v_mfma_f32_32x32x16_bf16 v[66:81], v[230:233], v[150:153], v[66:81]
	s_waitcnt lgkmcnt(1)
	v_mfma_f32_32x32x16_bf16 v[82:97], v[246:249], v[138:141], v[82:97]
	v_mfma_f32_32x32x16_bf16 v[66:81], v[246:249], v[154:157], v[66:81]
	s_waitcnt lgkmcnt(0)
	v_mfma_f32_32x32x16_bf16 v[82:97], v[240:243], v[142:145], v[82:97]
	v_mfma_f32_32x32x16_bf16 v[66:81], v[240:243], v[158:161], v[66:81]
	s_cmp_eq_u32 s101, 1
	s_cbranch_scc0 .Lpp_nb_l1
	s_barrier

.Lpp_nb_l2:
	s_cmp_eq_u32 s44, 63
	s_cbranch_scc0 .LBB0_1013
	s_waitcnt lgkmcnt(2)
	v_mfma_f32_32x32x16_bf16 v[50:65], v[226:229], v[170:173], v[50:65]
	ds_read_b128 v[240:243], v235 offset:4640
	v_mfma_f32_32x32x16_bf16 v[16:31], v[226:229], v[174:177], v[16:31]
	s_waitcnt lgkmcnt(2)
	v_mfma_f32_32x32x16_bf16 v[34:49], v[230:233], v[170:173], v[34:49]
	ds_read_b128 v[226:229], v235 offset:64
	v_mfma_f32_32x32x16_bf16 v[0:15], v[230:233], v[174:177], v[0:15]
	s_waitcnt lgkmcnt(2)
	v_mfma_f32_32x32x16_bf16 v[50:65], v[246:249], v[166:169], v[50:65]
	ds_read_b128 v[230:233], v235 offset:4672
	v_mfma_f32_32x32x16_bf16 v[16:31], v[246:249], v[162:165], v[16:31]
	s_waitcnt lgkmcnt(2)
	v_mfma_f32_32x32x16_bf16 v[34:49], v[240:243], v[166:169], v[34:49]
	ds_read_b128 v[246:249], v235 offset:96
	v_mfma_f32_32x32x16_bf16 v[0:15], v[240:243], v[162:165], v[0:15]
	s_waitcnt lgkmcnt(2)
	v_mfma_f32_32x32x16_bf16 v[50:65], v[226:229], v[186:189], v[50:65]
	ds_read_b128 v[240:243], v235 offset:4704
	v_mfma_f32_32x32x16_bf16 v[16:31], v[226:229], v[218:221], v[16:31]
	s_waitcnt lgkmcnt(2)
	v_mfma_f32_32x32x16_bf16 v[34:49], v[230:233], v[186:189], v[34:49]
	ds_read_b128 v[226:229], v234
	v_mfma_f32_32x32x16_bf16 v[0:15], v[230:233], v[218:221], v[0:15]
	s_waitcnt lgkmcnt(2)
	v_mfma_f32_32x32x16_bf16 v[50:65], v[246:249], v[190:193], v[50:65]
	ds_read_b128 v[230:233], v234 offset:32
	v_mfma_f32_32x32x16_bf16 v[16:31], v[246:249], v[222:225], v[16:31]
	s_waitcnt lgkmcnt(2)
	v_mfma_f32_32x32x16_bf16 v[34:49], v[240:243], v[190:193], v[34:49]
	ds_read_b128 v[246:249], v234 offset:64
	v_mfma_f32_32x32x16_bf16 v[0:15], v[240:243], v[222:225], v[0:15]
	s_waitcnt lgkmcnt(2)
	v_mfma_f32_32x32x16_bf16 v[114:129], v[226:229], v[130:133], 0
	ds_read_b128 v[240:243], v234 offset:96
	v_mfma_f32_32x32x16_bf16 v[98:113], v[226:229], v[146:149], 0
	s_waitcnt lgkmcnt(2)
	v_mfma_f32_32x32x16_bf16 v[114:129], v[230:233], v[134:137], v[114:129]
	ds_read_b128 v[226:229], v234 offset:4608
	v_mfma_f32_32x32x16_bf16 v[98:113], v[230:233], v[150:153], v[98:113]
	s_waitcnt lgkmcnt(2)
	v_mfma_f32_32x32x16_bf16 v[114:129], v[246:249], v[138:141], v[114:129]
	ds_read_b128 v[230:233], v234 offset:4640
	v_mfma_f32_32x32x16_bf16 v[98:113], v[246:249], v[154:157], v[98:113]
	s_waitcnt lgkmcnt(2)
	v_mfma_f32_32x32x16_bf16 v[114:129], v[240:243], v[142:145], v[114:129]
	ds_read_b128 v[246:249], v234 offset:4672
	v_mfma_f32_32x32x16_bf16 v[98:113], v[240:243], v[158:161], v[98:113]
	s_waitcnt lgkmcnt(2)
	v_mfma_f32_32x32x16_bf16 v[82:97], v[226:229], v[130:133], 0
	ds_read_b128 v[240:243], v234 offset:4704
	v_mfma_f32_32x32x16_bf16 v[66:81], v[226:229], v[146:149], 0
	s_waitcnt lgkmcnt(2)
	v_mfma_f32_32x32x16_bf16 v[82:97], v[230:233], v[134:137], v[82:97]
	v_mfma_f32_32x32x16_bf16 v[66:81], v[230:233], v[150:153], v[66:81]
	s_waitcnt lgkmcnt(1)
	v_mfma_f32_32x32x16_bf16 v[82:97], v[246:249], v[138:141], v[82:97]
	v_mfma_f32_32x32x16_bf16 v[66:81], v[246:249], v[154:157], v[66:81]
	s_waitcnt lgkmcnt(0)
	v_mfma_f32_32x32x16_bf16 v[82:97], v[240:243], v[142:145], v[82:97]
	v_mfma_f32_32x32x16_bf16 v[66:81], v[240:243], v[158:161], v[66:81]
	s_cmp_eq_u32 s101, 1
	s_cbranch_scc0 .Lpp_nb_p1
	s_barrier
